# P5 fused epilogue: x loads of each ladder step issued one step early (two steps in flight), waits count younger loads only; on top of v97
# baseline (speedup 1.0000x reference)
.LBB0_643:
	s_or_b64 exec, exec, s[46:47]
	v_add_u32_e32 v150, s35, v152
	v_ashrrev_i32_e32 v151, 31, v150
	v_lshlrev_b64 v[154:155], 11, v[150:151]
	v_lshl_add_u64 v[162:163], v[154:155], 0, v[146:147]
	s_waitcnt lgkmcnt(0)
	s_barrier
	v_lshl_add_u64 v[164:165], v[162:163], 2, s[36:37]
	global_load_dwordx4 v[236:239], v[164:165], off nt
	global_load_dwordx4 v[240:243], v[164:165], off offset:16 nt
	v_lshl_add_u32 v182, v152, 2, 0
	ds_read_b32 v166, v182 offset:8192
	v_lshl_add_u64 v[162:163], v[162:163], 1, s[52:53]
	s_mov_b32 s35, 0x102000
	s_mov_b64 s[10:11], 0x102000
	s_mov_b64 s[46:47], 0x104000
	s_waitcnt lgkmcnt(0)
	v_pk_mul_f32 v[126:127], v[126:127], v[166:167] op_sel_hi:[1,0]
	v_pk_mul_f32 v[128:129], v[128:129], v[166:167] op_sel_hi:[1,0]
	v_pk_mul_f32 v[122:123], v[122:123], v[166:167] op_sel_hi:[1,0]
	v_pk_mul_f32 v[124:125], v[124:125], v[166:167] op_sel_hi:[1,0]
	v_pk_mul_f32 v[170:171], v[118:119], v[166:167] op_sel_hi:[1,0]
	v_pk_mul_f32 v[118:119], v[120:121], v[166:167] op_sel_hi:[1,0]
	v_pk_mul_f32 v[172:173], v[114:115], v[166:167] op_sel_hi:[1,0]
	v_pk_mul_f32 v[114:115], v[116:117], v[166:167] op_sel_hi:[1,0]
	s_mov_b32 s43, 0x104000
	global_load_dwordx4 v[244:247], v[164:165], off offset:512 nt
	global_load_dwordx4 v[248:251], v[164:165], off offset:528 nt
	s_waitcnt vmcnt(3)
	v_mov_b32_e32 v154, v236
	v_mov_b32_e32 v155, v237
	v_mov_b32_e32 v156, v238
	v_mov_b32_e32 v157, v239
	v_pk_fma_f32 v[128:129], v[144:145], v[128:129], v[156:157]
	v_pk_fma_f32 v[152:153], v[142:143], v[126:127], v[154:155]
	s_waitcnt vmcnt(2)
	v_mov_b32_e32 v158, v240
	v_mov_b32_e32 v159, v241
	v_mov_b32_e32 v160, v242
	v_mov_b32_e32 v161, v243
	v_pk_fma_f32 v[124:125], v[140:141], v[124:125], v[160:161]
	v_pk_fma_f32 v[126:127], v[138:139], v[122:123], v[158:159]
	v_cvt_pk_bf16_f32 v154, v152, v153
	v_cvt_pk_bf16_f32 v155, v128, v129
	v_add_u32_e32 v122, 16, v150
	v_cvt_pk_bf16_f32 v156, v126, v127
	v_cvt_pk_bf16_f32 v157, v124, v125
	global_store_dwordx4 v[162:163], v[154:157], off
	v_ashrrev_i32_e32 v123, 31, v122
	v_lshlrev_b64 v[164:165], 11, v[122:123]
	v_lshl_add_u64 v[164:165], v[164:165], 0, v[146:147]
	v_lshl_add_u64 v[168:169], v[164:165], 2, s[36:37]
	v_lshl_add_u64 v[164:165], v[164:165], 1, s[52:53]
	v_mul_f32_e32 v187, v153, v153
	v_fmac_f32_e32 v187, v152, v152
	global_load_dwordx4 v[236:239], v[168:169], off nt
	global_load_dwordx4 v[240:243], v[168:169], off offset:16 nt
	s_waitcnt vmcnt(3)
	v_mov_b32_e32 v154, v244
	v_mov_b32_e32 v155, v245
	v_mov_b32_e32 v156, v246
	v_mov_b32_e32 v157, v247
	v_pk_fma_f32 v[118:119], v[136:137], v[118:119], v[156:157]
	v_pk_fma_f32 v[120:121], v[134:135], v[170:171], v[154:155]
	s_waitcnt vmcnt(2)
	v_mov_b32_e32 v158, v248
	v_mov_b32_e32 v159, v249
	v_mov_b32_e32 v160, v250
	v_mov_b32_e32 v161, v251
	v_pk_fma_f32 v[114:115], v[132:133], v[114:115], v[160:161]
	v_pk_fma_f32 v[116:117], v[130:131], v[172:173], v[158:159]
	v_cvt_pk_bf16_f32 v154, v120, v121
	v_cvt_pk_bf16_f32 v155, v118, v119
	s_nop 0
	v_cvt_pk_bf16_f32 v156, v116, v117
	v_cvt_pk_bf16_f32 v157, v114, v115
	global_store_dwordx4 v[162:163], v[154:157], off offset:256
	ds_read_b32 v166, v182 offset:8256
	s_waitcnt lgkmcnt(0)
	v_pk_mul_f32 v[110:111], v[110:111], v[166:167] op_sel_hi:[1,0]
	v_pk_mul_f32 v[112:113], v[112:113], v[166:167] op_sel_hi:[1,0]
	v_pk_mul_f32 v[106:107], v[106:107], v[166:167] op_sel_hi:[1,0]
	v_pk_mul_f32 v[108:109], v[108:109], v[166:167] op_sel_hi:[1,0]
	v_pk_mul_f32 v[172:173], v[102:103], v[166:167] op_sel_hi:[1,0]
	v_pk_mul_f32 v[102:103], v[104:105], v[166:167] op_sel_hi:[1,0]
	v_pk_mul_f32 v[174:175], v[98:99], v[166:167] op_sel_hi:[1,0]
	v_pk_mul_f32 v[98:99], v[100:101], v[166:167] op_sel_hi:[1,0]
	global_load_dwordx4 v[244:247], v[168:169], off offset:512 nt
	global_load_dwordx4 v[248:251], v[168:169], off offset:528 nt
	s_waitcnt vmcnt(3)
	v_mov_b32_e32 v154, v236
	v_mov_b32_e32 v155, v237
	v_mov_b32_e32 v156, v238
	v_mov_b32_e32 v157, v239
	v_pk_fma_f32 v[112:113], v[144:145], v[112:113], v[156:157]
	v_pk_fma_f32 v[154:155], v[142:143], v[110:111], v[154:155]
	s_waitcnt vmcnt(2)
	v_mov_b32_e32 v158, v240
	v_mov_b32_e32 v159, v241
	v_mov_b32_e32 v160, v242
	v_mov_b32_e32 v161, v243
	v_pk_fma_f32 v[108:109], v[140:141], v[108:109], v[160:161]
	v_pk_fma_f32 v[110:111], v[138:139], v[106:107], v[158:159]
	v_cvt_pk_bf16_f32 v156, v154, v155
	v_cvt_pk_bf16_f32 v157, v112, v113
	v_add_u32_e32 v106, 32, v150
	v_cvt_pk_bf16_f32 v158, v110, v111
	v_cvt_pk_bf16_f32 v159, v108, v109
	global_store_dwordx4 v[164:165], v[156:159], off
	v_ashrrev_i32_e32 v107, 31, v106
	v_lshlrev_b64 v[168:169], 11, v[106:107]
	v_lshl_add_u64 v[168:169], v[168:169], 0, v[146:147]
	v_lshl_add_u64 v[170:171], v[168:169], 2, s[36:37]
	v_lshl_add_u64 v[168:169], v[168:169], 1, s[52:53]
	global_load_dwordx4 v[236:239], v[170:171], off nt
	global_load_dwordx4 v[240:243], v[170:171], off offset:16 nt
	s_waitcnt vmcnt(3)
	v_mov_b32_e32 v156, v244
	v_mov_b32_e32 v157, v245
	v_mov_b32_e32 v158, v246
	v_mov_b32_e32 v159, v247
	v_pk_fma_f32 v[102:103], v[136:137], v[102:103], v[158:159]
	v_pk_fma_f32 v[104:105], v[134:135], v[172:173], v[156:157]
	s_waitcnt vmcnt(2)
	v_mov_b32_e32 v160, v248
	v_mov_b32_e32 v161, v249
	v_mov_b32_e32 v162, v250
	v_mov_b32_e32 v163, v251
	v_pk_fma_f32 v[98:99], v[132:133], v[98:99], v[162:163]
	v_pk_fma_f32 v[100:101], v[130:131], v[174:175], v[160:161]
	v_cvt_pk_bf16_f32 v156, v104, v105
	v_cvt_pk_bf16_f32 v157, v102, v103
	s_nop 0
	v_cvt_pk_bf16_f32 v158, v100, v101
	v_cvt_pk_bf16_f32 v159, v98, v99
	global_store_dwordx4 v[164:165], v[156:159], off offset:256
	ds_read_b32 v166, v182 offset:8320
	s_waitcnt lgkmcnt(0)
	v_pk_mul_f32 v[94:95], v[94:95], v[166:167] op_sel_hi:[1,0]
	v_pk_mul_f32 v[96:97], v[96:97], v[166:167] op_sel_hi:[1,0]
	v_pk_mul_f32 v[90:91], v[90:91], v[166:167] op_sel_hi:[1,0]
	v_pk_mul_f32 v[92:93], v[92:93], v[166:167] op_sel_hi:[1,0]
	v_pk_mul_f32 v[174:175], v[86:87], v[166:167] op_sel_hi:[1,0]
	v_pk_mul_f32 v[86:87], v[88:89], v[166:167] op_sel_hi:[1,0]
	v_pk_mul_f32 v[176:177], v[82:83], v[166:167] op_sel_hi:[1,0]
	v_pk_mul_f32 v[82:83], v[84:85], v[166:167] op_sel_hi:[1,0]
	global_load_dwordx4 v[244:247], v[170:171], off offset:512 nt
	global_load_dwordx4 v[248:251], v[170:171], off offset:528 nt
	s_waitcnt vmcnt(3)
	v_mov_b32_e32 v156, v236
	v_mov_b32_e32 v157, v237
	v_mov_b32_e32 v158, v238
	v_mov_b32_e32 v159, v239
	v_pk_fma_f32 v[96:97], v[144:145], v[96:97], v[158:159]
	v_pk_fma_f32 v[156:157], v[142:143], v[94:95], v[156:157]
	s_waitcnt vmcnt(2)
	v_mov_b32_e32 v160, v240
	v_mov_b32_e32 v161, v241
	v_mov_b32_e32 v162, v242
	v_mov_b32_e32 v163, v243
	v_pk_fma_f32 v[92:93], v[140:141], v[92:93], v[162:163]
	v_pk_fma_f32 v[94:95], v[138:139], v[90:91], v[160:161]
	v_cvt_pk_bf16_f32 v158, v156, v157
	v_cvt_pk_bf16_f32 v159, v96, v97
	v_add_u32_e32 v90, 48, v150
	v_cvt_pk_bf16_f32 v160, v94, v95
	v_cvt_pk_bf16_f32 v161, v92, v93
	global_store_dwordx4 v[168:169], v[158:161], off
	v_ashrrev_i32_e32 v91, 31, v90
	v_lshlrev_b64 v[170:171], 11, v[90:91]
	v_lshl_add_u64 v[170:171], v[170:171], 0, v[146:147]
	v_lshl_add_u64 v[172:173], v[170:171], 2, s[36:37]
	v_lshl_add_u64 v[170:171], v[170:171], 1, s[52:53]
	global_load_dwordx4 v[236:239], v[172:173], off nt
	global_load_dwordx4 v[240:243], v[172:173], off offset:16 nt
	s_waitcnt vmcnt(3)
	v_mov_b32_e32 v158, v244
	v_mov_b32_e32 v159, v245
	v_mov_b32_e32 v160, v246
	v_mov_b32_e32 v161, v247
	v_pk_fma_f32 v[86:87], v[136:137], v[86:87], v[160:161]
	v_pk_fma_f32 v[88:89], v[134:135], v[174:175], v[158:159]
	s_waitcnt vmcnt(2)
	v_mov_b32_e32 v162, v248
	v_mov_b32_e32 v163, v249
	v_mov_b32_e32 v164, v250
	v_mov_b32_e32 v165, v251
	v_pk_fma_f32 v[82:83], v[132:133], v[82:83], v[164:165]
	v_pk_fma_f32 v[84:85], v[130:131], v[176:177], v[162:163]
	v_cvt_pk_bf16_f32 v158, v88, v89
	v_cvt_pk_bf16_f32 v159, v86, v87
	s_nop 0
	v_cvt_pk_bf16_f32 v160, v84, v85
	v_cvt_pk_bf16_f32 v161, v82, v83
	global_store_dwordx4 v[168:169], v[158:161], off offset:256
	ds_read_b32 v168, v182 offset:8384
	s_waitcnt lgkmcnt(0)
	v_pk_mul_f32 v[78:79], v[78:79], v[168:169] op_sel_hi:[1,0]
	v_pk_mul_f32 v[80:81], v[80:81], v[168:169] op_sel_hi:[1,0]
	v_pk_mul_f32 v[74:75], v[74:75], v[168:169] op_sel_hi:[1,0]
	v_pk_mul_f32 v[76:77], v[76:77], v[168:169] op_sel_hi:[1,0]
	v_pk_mul_f32 v[176:177], v[70:71], v[168:169] op_sel_hi:[1,0]
	v_pk_mul_f32 v[70:71], v[72:73], v[168:169] op_sel_hi:[1,0]
	v_pk_mul_f32 v[178:179], v[66:67], v[168:169] op_sel_hi:[1,0]
	v_pk_mul_f32 v[66:67], v[68:69], v[168:169] op_sel_hi:[1,0]
	global_load_dwordx4 v[244:247], v[172:173], off offset:512 nt
	global_load_dwordx4 v[248:251], v[172:173], off offset:528 nt
	s_waitcnt vmcnt(3)
	v_mov_b32_e32 v158, v236
	v_mov_b32_e32 v159, v237
	v_mov_b32_e32 v160, v238
	v_mov_b32_e32 v161, v239
	v_pk_fma_f32 v[80:81], v[144:145], v[80:81], v[160:161]
	v_pk_fma_f32 v[158:159], v[142:143], v[78:79], v[158:159]
	s_waitcnt vmcnt(2)
	v_mov_b32_e32 v162, v240
	v_mov_b32_e32 v163, v241
	v_mov_b32_e32 v164, v242
	v_mov_b32_e32 v165, v243
	v_pk_fma_f32 v[76:77], v[140:141], v[76:77], v[164:165]
	v_pk_fma_f32 v[78:79], v[138:139], v[74:75], v[162:163]
	v_cvt_pk_bf16_f32 v160, v158, v159
	v_cvt_pk_bf16_f32 v161, v80, v81
	v_add_u32_e32 v74, 0x80, v150
	v_cvt_pk_bf16_f32 v162, v78, v79
	v_cvt_pk_bf16_f32 v163, v76, v77
	global_store_dwordx4 v[170:171], v[160:163], off
	v_ashrrev_i32_e32 v75, 31, v74
	v_lshlrev_b64 v[172:173], 11, v[74:75]
	v_lshl_add_u64 v[172:173], v[172:173], 0, v[146:147]
	v_lshl_add_u64 v[174:175], v[172:173], 2, s[36:37]
	v_lshl_add_u64 v[172:173], v[172:173], 1, s[52:53]
	global_load_dwordx4 v[236:239], v[174:175], off nt
	global_load_dwordx4 v[240:243], v[174:175], off offset:16 nt
	s_waitcnt vmcnt(3)
	v_mov_b32_e32 v160, v244
	v_mov_b32_e32 v161, v245
	v_mov_b32_e32 v162, v246
	v_mov_b32_e32 v163, v247
	v_pk_fma_f32 v[70:71], v[136:137], v[70:71], v[162:163]
	v_pk_fma_f32 v[72:73], v[134:135], v[176:177], v[160:161]
	s_waitcnt vmcnt(2)
	v_mov_b32_e32 v164, v248
	v_mov_b32_e32 v165, v249
	v_mov_b32_e32 v166, v250
	v_mov_b32_e32 v167, v251
	v_pk_fma_f32 v[66:67], v[132:133], v[66:67], v[166:167]
	v_pk_fma_f32 v[68:69], v[130:131], v[178:179], v[164:165]
	v_cvt_pk_bf16_f32 v160, v72, v73
	v_cvt_pk_bf16_f32 v161, v70, v71
	s_nop 0
	v_cvt_pk_bf16_f32 v162, v68, v69
	v_cvt_pk_bf16_f32 v163, v66, v67
	global_store_dwordx4 v[170:171], v[160:163], off offset:256
	ds_read_b32 v170, v182 offset:8704
	s_waitcnt lgkmcnt(0)
	v_pk_mul_f32 v[62:63], v[62:63], v[170:171] op_sel_hi:[1,0]
	v_pk_mul_f32 v[64:65], v[64:65], v[170:171] op_sel_hi:[1,0]
	v_pk_mul_f32 v[58:59], v[58:59], v[170:171] op_sel_hi:[1,0]
	v_pk_mul_f32 v[60:61], v[60:61], v[170:171] op_sel_hi:[1,0]
	v_pk_mul_f32 v[178:179], v[54:55], v[170:171] op_sel_hi:[1,0]
	v_pk_mul_f32 v[54:55], v[56:57], v[170:171] op_sel_hi:[1,0]
	v_pk_mul_f32 v[180:181], v[50:51], v[170:171] op_sel_hi:[1,0]
	v_pk_mul_f32 v[50:51], v[52:53], v[170:171] op_sel_hi:[1,0]
	global_load_dwordx4 v[244:247], v[174:175], off offset:512 nt
	global_load_dwordx4 v[248:251], v[174:175], off offset:528 nt
	s_waitcnt vmcnt(3)
	v_mov_b32_e32 v160, v236
	v_mov_b32_e32 v161, v237
	v_mov_b32_e32 v162, v238
	v_mov_b32_e32 v163, v239
	v_pk_fma_f32 v[64:65], v[144:145], v[64:65], v[162:163]
	v_pk_fma_f32 v[160:161], v[142:143], v[62:63], v[160:161]
	s_waitcnt vmcnt(2)
	v_mov_b32_e32 v164, v240
	v_mov_b32_e32 v165, v241
	v_mov_b32_e32 v166, v242
	v_mov_b32_e32 v167, v243
	v_pk_fma_f32 v[60:61], v[140:141], v[60:61], v[166:167]
	v_pk_fma_f32 v[62:63], v[138:139], v[58:59], v[164:165]
	v_cvt_pk_bf16_f32 v162, v160, v161
	v_cvt_pk_bf16_f32 v163, v64, v65
	v_add_u32_e32 v58, 0x90, v150
	v_cvt_pk_bf16_f32 v164, v62, v63
	v_cvt_pk_bf16_f32 v165, v60, v61
	global_store_dwordx4 v[172:173], v[162:165], off
	v_ashrrev_i32_e32 v59, 31, v58
	v_lshlrev_b64 v[174:175], 11, v[58:59]
	v_lshl_add_u64 v[174:175], v[174:175], 0, v[146:147]
	v_lshl_add_u64 v[176:177], v[174:175], 2, s[36:37]
	v_lshl_add_u64 v[174:175], v[174:175], 1, s[52:53]
	global_load_dwordx4 v[236:239], v[176:177], off nt
	global_load_dwordx4 v[240:243], v[176:177], off offset:16 nt
	s_waitcnt vmcnt(3)
	v_mov_b32_e32 v162, v244
	v_mov_b32_e32 v163, v245
	v_mov_b32_e32 v164, v246
	v_mov_b32_e32 v165, v247
	v_pk_fma_f32 v[54:55], v[136:137], v[54:55], v[164:165]
	v_pk_fma_f32 v[56:57], v[134:135], v[178:179], v[162:163]
	s_waitcnt vmcnt(2)
	v_mov_b32_e32 v166, v248
	v_mov_b32_e32 v167, v249
	v_mov_b32_e32 v168, v250
	v_mov_b32_e32 v169, v251
	v_pk_fma_f32 v[50:51], v[132:133], v[50:51], v[168:169]
	v_pk_fma_f32 v[52:53], v[130:131], v[180:181], v[166:167]
	v_cvt_pk_bf16_f32 v162, v56, v57
	v_cvt_pk_bf16_f32 v163, v54, v55
	s_nop 0
	v_cvt_pk_bf16_f32 v164, v52, v53
	v_cvt_pk_bf16_f32 v165, v50, v51
	global_store_dwordx4 v[172:173], v[162:165], off offset:256
	ds_read_b32 v172, v182 offset:8768
	s_waitcnt lgkmcnt(0)
	v_pk_mul_f32 v[46:47], v[46:47], v[172:173] op_sel_hi:[1,0]
	v_pk_mul_f32 v[48:49], v[48:49], v[172:173] op_sel_hi:[1,0]
	v_pk_mul_f32 v[42:43], v[42:43], v[172:173] op_sel_hi:[1,0]
	v_pk_mul_f32 v[44:45], v[44:45], v[172:173] op_sel_hi:[1,0]
	v_pk_mul_f32 v[188:189], v[34:35], v[172:173] op_sel_hi:[1,0]
	v_pk_mul_f32 v[34:35], v[36:37], v[172:173] op_sel_hi:[1,0]
	global_load_dwordx4 v[244:247], v[176:177], off offset:512 nt
	global_load_dwordx4 v[248:251], v[176:177], off offset:528 nt
	s_waitcnt vmcnt(3)
	v_mov_b32_e32 v162, v236
	v_mov_b32_e32 v163, v237
	v_mov_b32_e32 v164, v238
	v_mov_b32_e32 v165, v239
	v_pk_fma_f32 v[48:49], v[144:145], v[48:49], v[164:165]
	v_pk_fma_f32 v[162:163], v[142:143], v[46:47], v[162:163]
	s_waitcnt vmcnt(2)
	v_mov_b32_e32 v166, v240
	v_mov_b32_e32 v167, v241
	v_mov_b32_e32 v168, v242
	v_mov_b32_e32 v169, v243
	v_pk_fma_f32 v[44:45], v[140:141], v[44:45], v[168:169]
	v_pk_fma_f32 v[46:47], v[138:139], v[42:43], v[166:167]
	v_cvt_pk_bf16_f32 v164, v162, v163
	v_cvt_pk_bf16_f32 v165, v48, v49
	v_add_u32_e32 v42, 0xa0, v150
	v_cvt_pk_bf16_f32 v166, v46, v47
	v_cvt_pk_bf16_f32 v167, v44, v45
	global_store_dwordx4 v[174:175], v[164:167], off
	v_ashrrev_i32_e32 v43, 31, v42
	v_lshlrev_b64 v[176:177], 11, v[42:43]
	v_lshl_add_u64 v[178:179], v[176:177], 0, v[146:147]
	v_pk_mul_f32 v[176:177], v[38:39], v[172:173] op_sel_hi:[1,0]
	v_pk_mul_f32 v[38:39], v[40:41], v[172:173] op_sel_hi:[1,0]
	v_lshl_add_u64 v[180:181], v[178:179], 2, s[36:37]
	v_lshl_add_u64 v[190:191], v[178:179], 1, s[52:53]
	global_load_dwordx4 v[236:239], v[180:181], off nt
	global_load_dwordx4 v[240:243], v[180:181], off offset:16 nt
	s_waitcnt vmcnt(3)
	v_mov_b32_e32 v164, v244
	v_mov_b32_e32 v165, v245
	v_mov_b32_e32 v166, v246
	v_mov_b32_e32 v167, v247
	v_pk_fma_f32 v[38:39], v[136:137], v[38:39], v[166:167]
	v_pk_fma_f32 v[40:41], v[134:135], v[176:177], v[164:165]
	s_waitcnt vmcnt(2)
	v_mov_b32_e32 v168, v248
	v_mov_b32_e32 v169, v249
	v_mov_b32_e32 v170, v250
	v_mov_b32_e32 v171, v251
	v_pk_fma_f32 v[34:35], v[132:133], v[34:35], v[170:171]
	v_pk_fma_f32 v[36:37], v[130:131], v[188:189], v[168:169]
	v_cvt_pk_bf16_f32 v164, v40, v41
	v_cvt_pk_bf16_f32 v165, v38, v39
	s_nop 0
	v_cvt_pk_bf16_f32 v166, v36, v37
	v_cvt_pk_bf16_f32 v167, v34, v35
	global_store_dwordx4 v[174:175], v[164:167], off offset:256
	ds_read_b32 v188, v182 offset:8832
	s_waitcnt lgkmcnt(0)
	v_pk_mul_f32 v[30:31], v[30:31], v[188:189] op_sel_hi:[1,0]
	v_pk_mul_f32 v[32:33], v[32:33], v[188:189] op_sel_hi:[1,0]
	v_pk_mul_f32 v[26:27], v[26:27], v[188:189] op_sel_hi:[1,0]
	v_pk_mul_f32 v[28:29], v[28:29], v[188:189] op_sel_hi:[1,0]
	v_pk_mul_f32 v[22:23], v[22:23], v[188:189] op_sel_hi:[1,0]
	v_pk_mul_f32 v[24:25], v[24:25], v[188:189] op_sel_hi:[1,0]
	v_pk_mul_f32 v[18:19], v[18:19], v[188:189] op_sel_hi:[1,0]
	v_pk_mul_f32 v[20:21], v[20:21], v[188:189] op_sel_hi:[1,0]
	global_load_dwordx4 v[244:247], v[180:181], off offset:512 nt
	global_load_dwordx4 v[248:251], v[180:181], off offset:528 nt
	s_waitcnt vmcnt(3)
	v_mov_b32_e32 v164, v236
	v_mov_b32_e32 v165, v237
	v_mov_b32_e32 v166, v238
	v_mov_b32_e32 v167, v239
	v_pk_fma_f32 v[170:171], v[144:145], v[32:33], v[166:167]
	v_pk_fma_f32 v[172:173], v[142:143], v[30:31], v[164:165]
	s_waitcnt vmcnt(2)
	v_mov_b32_e32 v174, v240
	v_mov_b32_e32 v175, v241
	v_mov_b32_e32 v176, v242
	v_mov_b32_e32 v177, v243
	v_pk_fma_f32 v[166:167], v[140:141], v[28:29], v[176:177]
	v_pk_fma_f32 v[168:169], v[138:139], v[26:27], v[174:175]
	v_cvt_pk_bf16_f32 v26, v172, v173
	v_cvt_pk_bf16_f32 v27, v170, v171
	v_add_u32_e32 v164, 0xb0, v150
	v_cvt_pk_bf16_f32 v28, v168, v169
	v_cvt_pk_bf16_f32 v29, v166, v167
	global_store_dwordx4 v[190:191], v[26:29], off
	v_ashrrev_i32_e32 v165, 31, v164
	v_lshlrev_b64 v[174:175], 11, v[164:165]
	v_lshl_add_u64 v[192:193], v[174:175], 0, v[146:147]
	v_lshl_add_u64 v[194:195], v[192:193], 2, s[36:37]
	global_load_dwordx4 v[236:239], v[194:195], off nt
	global_load_dwordx4 v[240:243], v[194:195], off offset:16 nt
	s_waitcnt vmcnt(3)
	v_mov_b32_e32 v26, v244
	v_mov_b32_e32 v27, v245
	v_mov_b32_e32 v28, v246
	v_mov_b32_e32 v29, v247
	v_pk_fma_f32 v[178:179], v[136:137], v[24:25], v[28:29]
	v_pk_fma_f32 v[180:181], v[134:135], v[22:23], v[26:27]
	s_waitcnt vmcnt(2)
	v_mov_b32_e32 v30, v248
	v_mov_b32_e32 v31, v249
	v_mov_b32_e32 v32, v250
	v_mov_b32_e32 v33, v251
	v_pk_fma_f32 v[174:175], v[132:133], v[20:21], v[32:33]
	v_pk_fma_f32 v[176:177], v[130:131], v[18:19], v[30:31]
	v_cvt_pk_bf16_f32 v18, v180, v181
	v_cvt_pk_bf16_f32 v19, v178, v179
	v_lshl_add_u64 v[28:29], v[192:193], 1, s[52:53]
	v_cvt_pk_bf16_f32 v20, v176, v177
	v_cvt_pk_bf16_f32 v21, v174, v175
	global_store_dwordx4 v[190:191], v[18:21], off offset:256
	ds_read_b32 v26, v182 offset:8896
	s_waitcnt lgkmcnt(0)
	v_pk_mul_f32 v[14:15], v[14:15], v[26:27] op_sel_hi:[1,0]
	v_pk_mul_f32 v[16:17], v[16:17], v[26:27] op_sel_hi:[1,0]
	v_pk_mul_f32 v[10:11], v[10:11], v[26:27] op_sel_hi:[1,0]
	v_pk_mul_f32 v[12:13], v[12:13], v[26:27] op_sel_hi:[1,0]
	v_pk_mul_f32 v[6:7], v[6:7], v[26:27] op_sel_hi:[1,0]
	v_pk_mul_f32 v[8:9], v[8:9], v[26:27] op_sel_hi:[1,0]
	v_pk_mul_f32 v[2:3], v[2:3], v[26:27] op_sel_hi:[1,0]
	v_pk_mul_f32 v[4:5], v[4:5], v[26:27] op_sel_hi:[1,0]
	global_load_dwordx4 v[244:247], v[194:195], off offset:512 nt
	global_load_dwordx4 v[248:251], v[194:195], off offset:528 nt
	s_waitcnt vmcnt(3)
	v_mov_b32_e32 v18, v236
	v_mov_b32_e32 v19, v237
	v_mov_b32_e32 v20, v238
	v_mov_b32_e32 v21, v239
	v_pk_fma_f32 v[144:145], v[144:145], v[16:17], v[20:21]
	v_pk_fma_f32 v[142:143], v[142:143], v[14:15], v[18:19]
	s_waitcnt vmcnt(2)
	v_mov_b32_e32 v22, v240
	v_mov_b32_e32 v23, v241
	v_mov_b32_e32 v24, v242
	v_mov_b32_e32 v25, v243
	v_pk_fma_f32 v[140:141], v[140:141], v[12:13], v[24:25]
	v_pk_fma_f32 v[138:139], v[138:139], v[10:11], v[22:23]
	v_cvt_pk_bf16_f32 v10, v142, v143
	v_cvt_pk_bf16_f32 v11, v144, v145
	v_lshl_add_u64 v[18:19], v[146:147], 2, s[26:27]
	v_cvt_pk_bf16_f32 v12, v138, v139
	v_cvt_pk_bf16_f32 v13, v140, v141
	global_store_dwordx4 v[28:29], v[10:13], off
	v_add_co_u32_e32 v20, vcc, s35, v18
	v_lshl_add_u64 v[188:189], v[18:19], 0, s[10:11]
	s_nop 0
	v_addc_co_u32_e32 v21, vcc, 0, v19, vcc
	v_lshl_add_u64 v[190:191], v[18:19], 0, s[46:47]
	v_add_co_u32_e32 v18, vcc, s43, v18
	s_waitcnt vmcnt(1)
	v_mov_b32_e32 v10, v244
	v_mov_b32_e32 v11, v245
	v_mov_b32_e32 v12, v246
	v_mov_b32_e32 v13, v247
	v_pk_fma_f32 v[136:137], v[136:137], v[8:9], v[12:13]
	v_pk_fma_f32 v[134:135], v[134:135], v[6:7], v[10:11]
	s_waitcnt vmcnt(0)
	v_mov_b32_e32 v14, v248
	v_mov_b32_e32 v15, v249
	v_mov_b32_e32 v16, v250
	v_mov_b32_e32 v17, v251
	v_pk_fma_f32 v[132:133], v[132:133], v[4:5], v[16:17]
	v_pk_fma_f32 v[130:131], v[130:131], v[2:3], v[14:15]
	v_cvt_pk_bf16_f32 v2, v134, v135
	v_cvt_pk_bf16_f32 v3, v136, v137
	v_addc_co_u32_e32 v19, vcc, 0, v19, vcc
	v_cvt_pk_bf16_f32 v4, v130, v131
	v_cvt_pk_bf16_f32 v5, v132, v133
	global_store_dwordx4 v[28:29], v[2:5], off offset:256
	global_load_dwordx4 v[26:29], v[20:21], off
	global_load_dwordx4 v[30:33], v[18:19], off
	s_nop 0
	global_load_dwordx4 v[18:21], v[190:191], off offset:16
	global_load_dwordx4 v[2:5], v[188:189], off offset:528
	global_load_dwordx4 v[22:25], v[188:189], off offset:16
	global_load_dwordx4 v[10:13], v[188:189], off offset:512
	global_load_dwordx4 v[6:9], v[190:191], off offset:528
	global_load_dwordx4 v[14:17], v[190:191], off offset:512
	v_mul_f32_e32 v188, v129, v129
	v_fmac_f32_e32 v188, v128, v128
	v_add_f32_e32 v187, v187, v188
	v_mul_f32_e32 v188, v127, v127
	v_mul_f32_e32 v189, v125, v125
	v_fmac_f32_e32 v188, v126, v126
	v_fmac_f32_e32 v189, v124, v124
	v_add_f32_e32 v188, v188, v189
	v_add_f32_e32 v187, v187, v188
	v_mul_f32_e32 v188, v121, v121
	v_mul_f32_e32 v189, v119, v119
	v_fmac_f32_e32 v188, v120, v120
	v_fmac_f32_e32 v189, v118, v118
	v_add_f32_e32 v188, v188, v189
	v_add_f32_e32 v187, v187, v188
	v_mul_f32_e32 v188, v117, v117
	v_mul_f32_e32 v189, v115, v115
	v_fmac_f32_e32 v188, v116, v116
	v_fmac_f32_e32 v189, v114, v114
	v_add_f32_e32 v188, v188, v189
	v_add_f32_e32 v187, v187, v188
	ds_bpermute_b32 v188, v183, v187
	s_waitcnt lgkmcnt(0)
	v_add_f32_e32 v187, v187, v188
	ds_bpermute_b32 v188, v184, v187
	s_and_saveexec_b64 s[10:11], s[8:9]
	s_cbranch_execz .LBB0_645
	s_lshl_b32 s35, s29, 10
	s_add_i32 s35, s13, s35
	v_lshl_add_u32 v189, v1, 4, s35
	s_waitcnt lgkmcnt(0)
	v_add_f32_e32 v187, v187, v188
	ds_write_b32 v189, v187
